# EpiH1 gelu: three constant multiplies of the sigmoid argument folded into one fmaak (x*(c1+c2*x*x)), 5 -> 3 VALU per element
# speedup vs baseline: 1.0028x; 1.0028x over previous
.LBB0_519:
	v_mov_b32_e32 v255, 0xbdd2d3e7
	s_add_i32 s26, s26, 1
	s_mul_i32 s0, s26, s31
	s_mul_hi_u32 s1, s26, s97
	s_add_i32 s1, s1, s0
	s_mul_i32 s0, s26, s97
	s_add_u32 s78, s0, s96
	s_addc_u32 s79, s1, s54
	v_cmp_gt_i64_e32 vcc, s[78:79], v[146:147]
	v_cmp_lt_i64_e64 s[0:1], s[78:79], v[144:145]
	s_cbranch_vccnz .LBB0_521
	s_ashr_i32 s5, s78, 31
	s_lshr_b32 s5, s5, 29
	s_add_i32 s5, s78, s5
	s_ashr_i32 s8, s5, 3
	s_and_b32 s5, s5, -8
	s_sub_i32 s5, s78, s5
	s_cmp_lt_i32 s5, 0
	s_movk_i32 s9, 0xa1
	s_cselect_b32 s9, s9, 0xa0
	s_mul_i32 s5, s5, s9
	s_add_i32 s5, s5, s8
	s_mul_hi_i32 s8, s5, 0x66666667
	s_lshr_b32 s9, s8, 31
	s_ashr_i32 s8, s8, 5
	s_add_i32 s8, s8, s9
	s_lshl_b32 s9, s8, 3
	s_sub_i32 s10, 0x80, s9
	s_min_i32 s10, s10, 8
	s_abs_i32 s11, s10
	v_cvt_f32_u32_e32 v0, s11
	s_sub_i32 s15, 0, s11
	s_mulk_i32 s8, 0x50
	s_sub_i32 s5, s5, s8
	v_rcp_iflag_f32_e32 v0, v0
	s_abs_i32 s8, s5
	s_xor_b32 s14, s5, s10
	s_ashr_i32 s14, s14, 31
	v_mul_f32_e32 v0, 0x4f7ffffe, v0
	v_cvt_u32_f32_e32 v0, v0
	s_nop 0
	v_readfirstlane_b32 s24, v0
	s_mul_i32 s15, s15, s24
	s_mul_hi_u32 s15, s24, s15
	s_add_i32 s24, s24, s15
	s_mul_hi_u32 s15, s8, s24
	s_mul_i32 s24, s15, s11
	s_sub_i32 s8, s8, s24
	s_add_i32 s25, s15, 1
	s_sub_i32 s24, s8, s11
	s_cmp_ge_u32 s8, s11
	s_cselect_b32 s15, s25, s15
	s_cselect_b32 s8, s24, s8
	s_add_i32 s24, s15, 1
	s_cmp_ge_u32 s8, s11
	s_cselect_b32 s8, s24, s15
	s_xor_b32 s8, s8, s14
	s_sub_i32 s68, s8, s14
	s_mul_i32 s8, s68, s10
	s_sub_i32 s5, s5, s8
	s_add_i32 s76, s9, s5

.LBB0_538:
	s_andn2_b64 vcc, exec, s[90:91]
	s_cbranch_vccnz .LBB0_543
	v_mul_f32_e32 v128, v124, v124
	v_mul_f32_e32 v129, v120, v120
	v_mul_f32_e32 v130, v125, v125
	v_mul_f32_e32 v131, v121, v121
	v_mul_f32_e32 v158, v126, v126
	v_mul_f32_e32 v159, v122, v122
	v_mul_f32_e32 v160, v127, v127
	v_mul_f32_e32 v161, v123, v123
	v_fmaak_f32 v128, v255, v128, 0xc0135761
	v_fmaak_f32 v129, v255, v129, 0xc0135761
	v_fmaak_f32 v130, v255, v130, 0xc0135761
	v_fmaak_f32 v131, v255, v131, 0xc0135761
	v_fmaak_f32 v158, v255, v158, 0xc0135761
	v_fmaak_f32 v159, v255, v159, 0xc0135761
	v_fmaak_f32 v160, v255, v160, 0xc0135761
	v_fmaak_f32 v161, v255, v161, 0xc0135761
	v_mul_f32_e32 v128, v124, v128
	v_mul_f32_e32 v129, v120, v129
	v_mul_f32_e32 v130, v125, v130
	v_mul_f32_e32 v131, v121, v131
	v_mul_f32_e32 v158, v126, v158
	v_mul_f32_e32 v159, v122, v159
	v_mul_f32_e32 v160, v127, v160
	v_mul_f32_e32 v161, v123, v161
	v_exp_f32_e32 v128, v128
	v_exp_f32_e32 v129, v129
	v_exp_f32_e32 v130, v130
	v_exp_f32_e32 v131, v131
	v_exp_f32_e32 v158, v158
	v_exp_f32_e32 v159, v159
	v_exp_f32_e32 v160, v160
	v_exp_f32_e32 v161, v161
	v_add_f32_e32 v128, 1.0, v128
	v_add_f32_e32 v129, 1.0, v129
	v_add_f32_e32 v130, 1.0, v130
	v_add_f32_e32 v131, 1.0, v131
	v_add_f32_e32 v158, 1.0, v158
	v_add_f32_e32 v159, 1.0, v159
	v_add_f32_e32 v160, 1.0, v160
	v_add_f32_e32 v161, 1.0, v161
	v_rcp_f32_e32 v128, v128
	v_rcp_f32_e32 v129, v129
	v_rcp_f32_e32 v130, v130
	v_rcp_f32_e32 v131, v131
	v_rcp_f32_e32 v158, v158
	v_rcp_f32_e32 v159, v159
	v_rcp_f32_e32 v160, v160
	v_rcp_f32_e32 v161, v161
	v_mul_f32_e32 v128, v124, v128
	v_mul_f32_e32 v129, v120, v129
	v_mul_f32_e32 v130, v125, v130
	v_mul_f32_e32 v131, v121, v131
	v_mul_f32_e32 v158, v126, v158
	v_mul_f32_e32 v159, v122, v159
	v_mul_f32_e32 v160, v127, v160
	v_mul_f32_e32 v161, v123, v161
	v_cvt_pk_bf16_f32 v168, v128, v130
	v_cvt_pk_bf16_f32 v169, v158, v160
	v_cvt_pk_bf16_f32 v170, v129, v131
	v_cvt_pk_bf16_f32 v171, v159, v161
	v_lshl_add_u64 v[180:181], v[148:149], 1, v[156:157]
	global_store_dwordx4 v[180:181], v[168:171], off
	v_mul_f32_e32 v172, v118, v118
	v_mul_f32_e32 v173, v114, v114
	v_mul_f32_e32 v168, v116, v116
	v_mul_f32_e32 v169, v112, v112
	v_mul_f32_e32 v170, v117, v117
	v_mul_f32_e32 v171, v113, v113
	v_mul_f32_e32 v174, v119, v119
	v_mul_f32_e32 v175, v115, v115
	v_fmaak_f32 v168, v255, v168, 0xc0135761
	v_fmaak_f32 v169, v255, v169, 0xc0135761
	v_fmaak_f32 v170, v255, v170, 0xc0135761
	v_fmaak_f32 v171, v255, v171, 0xc0135761
	v_fmaak_f32 v172, v255, v172, 0xc0135761
	v_fmaak_f32 v173, v255, v173, 0xc0135761
	v_fmaak_f32 v174, v255, v174, 0xc0135761
	v_fmaak_f32 v175, v255, v175, 0xc0135761
	v_mul_f32_e32 v168, v116, v168
	v_mul_f32_e32 v169, v112, v169
	v_mul_f32_e32 v170, v117, v170
	v_mul_f32_e32 v171, v113, v171
	v_mul_f32_e32 v172, v118, v172
	v_mul_f32_e32 v173, v114, v173
	v_mul_f32_e32 v174, v119, v174
	v_mul_f32_e32 v175, v115, v175
	v_exp_f32_e32 v168, v168
	v_exp_f32_e32 v169, v169
	v_exp_f32_e32 v170, v170
	v_exp_f32_e32 v171, v171
	v_exp_f32_e32 v172, v172
	v_exp_f32_e32 v173, v173
	v_exp_f32_e32 v174, v174
	v_exp_f32_e32 v175, v175
	v_add_f32_e32 v168, 1.0, v168
	v_add_f32_e32 v169, 1.0, v169
	v_add_f32_e32 v170, 1.0, v170
	v_add_f32_e32 v171, 1.0, v171
	v_add_f32_e32 v172, 1.0, v172
	v_add_f32_e32 v173, 1.0, v173
	v_add_f32_e32 v174, 1.0, v174
	v_add_f32_e32 v175, 1.0, v175
	v_rcp_f32_e32 v168, v168
	v_rcp_f32_e32 v169, v169
	v_rcp_f32_e32 v170, v170
	v_rcp_f32_e32 v171, v171
	v_rcp_f32_e32 v172, v172
	v_rcp_f32_e32 v173, v173
	v_rcp_f32_e32 v174, v174
	v_rcp_f32_e32 v175, v175
	v_mul_f32_e32 v168, v116, v168
	v_mul_f32_e32 v169, v112, v169
	v_mul_f32_e32 v170, v117, v170
	v_mul_f32_e32 v171, v113, v171
	v_mul_f32_e32 v172, v118, v172
	v_mul_f32_e32 v173, v114, v173
	v_mul_f32_e32 v174, v119, v174
	v_mul_f32_e32 v175, v115, v175
	s_andn2_b64 vcc, exec, s[84:85]
	v_cvt_pk_bf16_f32 v176, v168, v170
	v_cvt_pk_bf16_f32 v177, v172, v174
	v_cvt_pk_bf16_f32 v178, v169, v171
	v_cvt_pk_bf16_f32 v179, v173, v175
	global_store_dwordx4 v[180:181], v[176:179], off offset:256
	s_cbranch_vccnz .LBB0_543
	s_nop 0
	v_mul_f32_e32 v176, v130, v130
	v_mul_f32_e32 v177, v160, v160
	v_fmac_f32_e32 v176, v128, v128
	v_fmac_f32_e32 v177, v158, v158
	v_add_f32_e32 v176, v176, v177
	v_mul_f32_e32 v177, v131, v131
	v_mul_f32_e32 v178, v161, v161
	v_fmac_f32_e32 v177, v129, v129
	v_fmac_f32_e32 v178, v159, v159
	v_add_f32_e32 v128, v128, v130
	v_add_f32_e32 v130, v158, v160
	v_add_f32_e32 v177, v177, v178
	v_add_f32_e32 v128, v128, v130
	v_add_f32_e32 v129, v129, v131
	v_add_f32_e32 v130, v159, v161
	v_add_f32_e32 v176, v176, v177
	v_mul_f32_e32 v177, v170, v170
	v_mul_f32_e32 v178, v174, v174
	v_add_f32_e32 v129, v129, v130
	v_fmac_f32_e32 v177, v168, v168
	v_fmac_f32_e32 v178, v172, v172
	v_add_f32_e32 v128, v128, v129
	v_add_f32_e32 v129, v168, v170
	v_add_f32_e32 v130, v172, v174
	v_add_f32_e32 v177, v177, v178
	v_mul_f32_e32 v178, v171, v171
	v_mul_f32_e32 v179, v175, v175
	v_add_f32_e32 v129, v129, v130
	v_add_f32_e32 v130, v169, v171
	v_add_f32_e32 v131, v173, v175
	v_fmac_f32_e32 v178, v169, v169
	v_fmac_f32_e32 v179, v173, v173
	v_add_f32_e32 v130, v130, v131
	v_add_f32_e32 v129, v129, v130
	v_add_f32_e32 v130, v178, v179
	v_add_f32_e32 v128, 0, v128
	v_add_f32_e32 v130, v177, v130
	v_add_f32_e32 v128, v128, v129
	v_add_f32_e32 v131, v176, v130
	ds_swizzle_b32 v129, v128 offset:swizzle(SWAP,16)
	ds_swizzle_b32 v158, v131 offset:swizzle(SWAP,16)
	s_waitcnt lgkmcnt(0)
	v_add_f32_e32 v128, v128, v129
	v_add_f32_e32 v129, v131, v158
	v_mov_b32_e32 v130, v128
	v_mov_b32_e32 v131, v129
	s_nop 0
	v_permlane32_swap_b32_e32 v128, v130
	v_permlane32_swap_b32_e32 v129, v131
	s_and_saveexec_b64 s[90:91], s[4:5]
	s_cbranch_execz .LBB0_542
	v_pk_add_f32 v[128:129], v[128:129], v[130:131]
	v_lshlrev_b64 v[130:131], 6, v[154:155]
	v_lshl_add_u64 v[130:131], s[18:19], 0, v[130:131]
	v_lshl_add_u64 v[130:131], s[52:53], 3, v[130:131]
	s_lshl_b32 s8, s40, 3
	s_mov_b32 s9, s53
	v_lshl_add_u64 v[130:131], v[130:131], 0, s[8:9]
	global_store_dwordx2 v[130:131], v[128:129], off

.LBB0_559:
	s_andn2_b64 vcc, exec, s[90:91]
	s_cbranch_vccnz .LBB0_564
	v_mul_f32_e32 v112, v108, v108
	v_mul_f32_e32 v113, v104, v104
	v_mul_f32_e32 v114, v109, v109
	v_mul_f32_e32 v115, v105, v105
	v_mul_f32_e32 v120, v110, v110
	v_mul_f32_e32 v121, v106, v106
	v_mul_f32_e32 v122, v111, v111
	v_mul_f32_e32 v123, v107, v107
	v_fmaak_f32 v112, v255, v112, 0xc0135761
	v_fmaak_f32 v113, v255, v113, 0xc0135761
	v_fmaak_f32 v114, v255, v114, 0xc0135761
	v_fmaak_f32 v115, v255, v115, 0xc0135761
	v_fmaak_f32 v120, v255, v120, 0xc0135761
	v_fmaak_f32 v121, v255, v121, 0xc0135761
	v_fmaak_f32 v122, v255, v122, 0xc0135761
	v_fmaak_f32 v123, v255, v123, 0xc0135761
	v_mul_f32_e32 v112, v108, v112
	v_mul_f32_e32 v113, v104, v113
	v_mul_f32_e32 v114, v109, v114
	v_mul_f32_e32 v115, v105, v115
	v_mul_f32_e32 v120, v110, v120
	v_mul_f32_e32 v121, v106, v121
	v_mul_f32_e32 v122, v111, v122
	v_mul_f32_e32 v123, v107, v123
	v_exp_f32_e32 v112, v112
	v_exp_f32_e32 v113, v113
	v_exp_f32_e32 v114, v114
	v_exp_f32_e32 v115, v115
	v_exp_f32_e32 v120, v120
	v_exp_f32_e32 v121, v121
	v_exp_f32_e32 v122, v122
	v_exp_f32_e32 v123, v123
	v_add_f32_e32 v112, 1.0, v112
	v_add_f32_e32 v113, 1.0, v113
	v_add_f32_e32 v114, 1.0, v114
	v_add_f32_e32 v115, 1.0, v115
	v_add_f32_e32 v120, 1.0, v120
	v_add_f32_e32 v121, 1.0, v121
	v_add_f32_e32 v122, 1.0, v122
	v_add_f32_e32 v123, 1.0, v123
	v_rcp_f32_e32 v112, v112
	v_rcp_f32_e32 v113, v113
	v_rcp_f32_e32 v114, v114
	v_rcp_f32_e32 v115, v115
	v_rcp_f32_e32 v120, v120
	v_rcp_f32_e32 v121, v121
	v_rcp_f32_e32 v122, v122
	v_rcp_f32_e32 v123, v123
	v_mul_f32_e32 v112, v108, v112
	v_mul_f32_e32 v113, v104, v113
	v_mul_f32_e32 v114, v109, v114
	v_mul_f32_e32 v115, v105, v115
	v_mul_f32_e32 v120, v110, v120
	v_mul_f32_e32 v121, v106, v121
	v_mul_f32_e32 v122, v111, v122
	v_mul_f32_e32 v123, v107, v123
	v_cvt_pk_bf16_f32 v124, v112, v114
	v_cvt_pk_bf16_f32 v125, v120, v122
	v_cvt_pk_bf16_f32 v126, v113, v115
	v_cvt_pk_bf16_f32 v127, v121, v123
	v_lshl_add_u64 v[160:161], v[148:149], 1, v[118:119]
	global_store_dwordx4 v[160:161], v[124:127], off
	v_mul_f32_e32 v128, v102, v102
	v_mul_f32_e32 v129, v98, v98
	v_mul_f32_e32 v124, v100, v100
	v_mul_f32_e32 v125, v96, v96
	v_mul_f32_e32 v126, v101, v101
	v_mul_f32_e32 v127, v97, v97
	v_mul_f32_e32 v130, v103, v103
	v_mul_f32_e32 v131, v99, v99
	v_fmaak_f32 v124, v255, v124, 0xc0135761
	v_fmaak_f32 v125, v255, v125, 0xc0135761
	v_fmaak_f32 v126, v255, v126, 0xc0135761
	v_fmaak_f32 v127, v255, v127, 0xc0135761
	v_fmaak_f32 v128, v255, v128, 0xc0135761
	v_fmaak_f32 v129, v255, v129, 0xc0135761
	v_fmaak_f32 v130, v255, v130, 0xc0135761
	v_fmaak_f32 v131, v255, v131, 0xc0135761
	v_mul_f32_e32 v124, v100, v124
	v_mul_f32_e32 v125, v96, v125
	v_mul_f32_e32 v126, v101, v126
	v_mul_f32_e32 v127, v97, v127
	v_mul_f32_e32 v128, v102, v128
	v_mul_f32_e32 v129, v98, v129
	v_mul_f32_e32 v130, v103, v130
	v_mul_f32_e32 v131, v99, v131
	v_exp_f32_e32 v124, v124
	v_exp_f32_e32 v125, v125
	v_exp_f32_e32 v126, v126
	v_exp_f32_e32 v127, v127
	v_exp_f32_e32 v128, v128
	v_exp_f32_e32 v129, v129
	v_exp_f32_e32 v130, v130
	v_exp_f32_e32 v131, v131
	v_add_f32_e32 v124, 1.0, v124
	v_add_f32_e32 v125, 1.0, v125
	v_add_f32_e32 v126, 1.0, v126
	v_add_f32_e32 v127, 1.0, v127
	v_add_f32_e32 v128, 1.0, v128
	v_add_f32_e32 v129, 1.0, v129
	v_add_f32_e32 v130, 1.0, v130
	v_add_f32_e32 v131, 1.0, v131
	v_rcp_f32_e32 v124, v124
	v_rcp_f32_e32 v125, v125
	v_rcp_f32_e32 v126, v126
	v_rcp_f32_e32 v127, v127
	v_rcp_f32_e32 v128, v128
	v_rcp_f32_e32 v129, v129
	v_rcp_f32_e32 v130, v130
	v_rcp_f32_e32 v131, v131
	v_mul_f32_e32 v124, v100, v124
	v_mul_f32_e32 v125, v96, v125
	v_mul_f32_e32 v126, v101, v126
	v_mul_f32_e32 v127, v97, v127
	v_mul_f32_e32 v128, v102, v128
	v_mul_f32_e32 v129, v98, v129
	v_mul_f32_e32 v130, v103, v130
	v_mul_f32_e32 v131, v99, v131
	s_andn2_b64 vcc, exec, s[84:85]
	v_cvt_pk_bf16_f32 v156, v124, v126
	v_cvt_pk_bf16_f32 v157, v128, v130
	v_cvt_pk_bf16_f32 v158, v125, v127
	v_cvt_pk_bf16_f32 v159, v129, v131
	global_store_dwordx4 v[160:161], v[156:159], off offset:256
	s_cbranch_vccnz .LBB0_564
	v_mul_f32_e32 v155, v114, v114
	v_mul_f32_e32 v156, v122, v122
	v_fmac_f32_e32 v155, v112, v112
	v_fmac_f32_e32 v156, v120, v120
	v_add_f32_e32 v155, v155, v156
	v_mul_f32_e32 v156, v115, v115
	v_mul_f32_e32 v157, v123, v123
	v_fmac_f32_e32 v156, v113, v113
	v_fmac_f32_e32 v157, v121, v121
	v_add_f32_e32 v112, v112, v114
	v_add_f32_e32 v114, v120, v122
	v_add_f32_e32 v156, v156, v157
	v_add_f32_e32 v112, v112, v114
	v_add_f32_e32 v113, v113, v115
	v_add_f32_e32 v114, v121, v123
	v_add_f32_e32 v155, v155, v156
	v_mul_f32_e32 v156, v126, v126
	v_mul_f32_e32 v157, v130, v130
	v_add_f32_e32 v113, v113, v114
	v_fmac_f32_e32 v156, v124, v124
	v_fmac_f32_e32 v157, v128, v128
	v_add_f32_e32 v112, v112, v113
	v_add_f32_e32 v113, v124, v126
	v_add_f32_e32 v114, v128, v130
	v_add_f32_e32 v156, v156, v157
	v_mul_f32_e32 v157, v127, v127
	v_mul_f32_e32 v158, v131, v131
	v_add_f32_e32 v113, v113, v114
	v_add_f32_e32 v114, v125, v127
	v_add_f32_e32 v115, v129, v131
	v_fmac_f32_e32 v157, v125, v125
	v_fmac_f32_e32 v158, v129, v129
	v_add_f32_e32 v114, v114, v115
	v_add_f32_e32 v113, v113, v114
	v_add_f32_e32 v114, v157, v158
	v_add_f32_e32 v112, 0, v112
	v_add_f32_e32 v114, v156, v114
	v_add_f32_e32 v112, v112, v113
	v_add_f32_e32 v115, v155, v114
	ds_swizzle_b32 v113, v112 offset:swizzle(SWAP,16)
	ds_swizzle_b32 v120, v115 offset:swizzle(SWAP,16)
	s_waitcnt lgkmcnt(0)
	v_add_f32_e32 v112, v112, v113
	v_add_f32_e32 v113, v115, v120
	v_mov_b32_e32 v114, v112
	v_mov_b32_e32 v115, v113
	s_nop 0
	v_permlane32_swap_b32_e32 v112, v114
	v_permlane32_swap_b32_e32 v113, v115
	s_and_saveexec_b64 s[90:91], s[4:5]
	s_cbranch_execz .LBB0_563
	v_pk_add_f32 v[112:113], v[112:113], v[114:115]
	v_lshlrev_b64 v[114:115], 6, v[116:117]
	v_lshl_add_u64 v[114:115], s[18:19], 0, v[114:115]
	v_lshl_add_u64 v[114:115], s[52:53], 3, v[114:115]
	s_lshl_b32 s8, s40, 3
	s_mov_b32 s9, s53
	v_lshl_add_u64 v[114:115], v[114:115], 0, s[8:9]
	global_store_dwordx2 v[114:115], v[112:113], off

.LBB0_582:
	s_andn2_b64 vcc, exec, s[90:91]
	s_cbranch_vccnz .LBB0_587
	v_mul_f32_e32 v96, v92, v92
	v_mul_f32_e32 v97, v88, v88
	v_mul_f32_e32 v98, v93, v93
	v_mul_f32_e32 v99, v89, v89
	v_mul_f32_e32 v104, v94, v94
	v_mul_f32_e32 v105, v90, v90
	v_mul_f32_e32 v106, v95, v95
	v_mul_f32_e32 v107, v91, v91
	v_fmaak_f32 v96, v255, v96, 0xc0135761
	v_fmaak_f32 v97, v255, v97, 0xc0135761
	v_fmaak_f32 v98, v255, v98, 0xc0135761
	v_fmaak_f32 v99, v255, v99, 0xc0135761
	v_fmaak_f32 v104, v255, v104, 0xc0135761
	v_fmaak_f32 v105, v255, v105, 0xc0135761
	v_fmaak_f32 v106, v255, v106, 0xc0135761
	v_fmaak_f32 v107, v255, v107, 0xc0135761
	v_mul_f32_e32 v96, v92, v96
	v_mul_f32_e32 v97, v88, v97
	v_mul_f32_e32 v98, v93, v98
	v_mul_f32_e32 v99, v89, v99
	v_mul_f32_e32 v104, v94, v104
	v_mul_f32_e32 v105, v90, v105
	v_mul_f32_e32 v106, v95, v106
	v_mul_f32_e32 v107, v91, v107
	v_exp_f32_e32 v96, v96
	v_exp_f32_e32 v97, v97
	v_exp_f32_e32 v98, v98
	v_exp_f32_e32 v99, v99
	v_exp_f32_e32 v104, v104
	v_exp_f32_e32 v105, v105
	v_exp_f32_e32 v106, v106
	v_exp_f32_e32 v107, v107
	v_add_f32_e32 v96, 1.0, v96
	v_add_f32_e32 v97, 1.0, v97
	v_add_f32_e32 v98, 1.0, v98
	v_add_f32_e32 v99, 1.0, v99
	v_add_f32_e32 v104, 1.0, v104
	v_add_f32_e32 v105, 1.0, v105
	v_add_f32_e32 v106, 1.0, v106
	v_add_f32_e32 v107, 1.0, v107
	v_rcp_f32_e32 v96, v96
	v_rcp_f32_e32 v97, v97
	v_rcp_f32_e32 v98, v98
	v_rcp_f32_e32 v99, v99
	v_rcp_f32_e32 v104, v104
	v_rcp_f32_e32 v105, v105
	v_rcp_f32_e32 v106, v106
	v_rcp_f32_e32 v107, v107
	v_mul_f32_e32 v96, v92, v96
	v_mul_f32_e32 v97, v88, v97
	v_mul_f32_e32 v98, v93, v98
	v_mul_f32_e32 v99, v89, v99
	v_mul_f32_e32 v104, v94, v104
	v_mul_f32_e32 v105, v90, v105
	v_mul_f32_e32 v106, v95, v106
	v_mul_f32_e32 v107, v91, v107
	v_cvt_pk_bf16_f32 v108, v96, v98
	v_cvt_pk_bf16_f32 v109, v104, v106
	v_cvt_pk_bf16_f32 v110, v97, v99
	v_cvt_pk_bf16_f32 v111, v105, v107
	v_lshl_add_u64 v[120:121], v[148:149], 1, v[102:103]
	global_store_dwordx4 v[120:121], v[108:111], off
	v_mul_f32_e32 v112, v86, v86
	v_mul_f32_e32 v113, v82, v82
	v_mul_f32_e32 v108, v84, v84
	v_mul_f32_e32 v109, v80, v80
	v_mul_f32_e32 v110, v85, v85
	v_mul_f32_e32 v111, v81, v81
	v_mul_f32_e32 v114, v87, v87
	v_mul_f32_e32 v115, v83, v83
	v_fmaak_f32 v108, v255, v108, 0xc0135761
	v_fmaak_f32 v109, v255, v109, 0xc0135761
	v_fmaak_f32 v110, v255, v110, 0xc0135761
	v_fmaak_f32 v111, v255, v111, 0xc0135761
	v_fmaak_f32 v112, v255, v112, 0xc0135761
	v_fmaak_f32 v113, v255, v113, 0xc0135761
	v_fmaak_f32 v114, v255, v114, 0xc0135761
	v_fmaak_f32 v115, v255, v115, 0xc0135761
	v_mul_f32_e32 v108, v84, v108
	v_mul_f32_e32 v109, v80, v109
	v_mul_f32_e32 v110, v85, v110
	v_mul_f32_e32 v111, v81, v111
	v_mul_f32_e32 v112, v86, v112
	v_mul_f32_e32 v113, v82, v113
	v_mul_f32_e32 v114, v87, v114
	v_mul_f32_e32 v115, v83, v115
	v_exp_f32_e32 v108, v108
	v_exp_f32_e32 v109, v109
	v_exp_f32_e32 v110, v110
	v_exp_f32_e32 v111, v111
	v_exp_f32_e32 v112, v112
	v_exp_f32_e32 v113, v113
	v_exp_f32_e32 v114, v114
	v_exp_f32_e32 v115, v115
	v_add_f32_e32 v108, 1.0, v108
	v_add_f32_e32 v109, 1.0, v109
	v_add_f32_e32 v110, 1.0, v110
	v_add_f32_e32 v111, 1.0, v111
	v_add_f32_e32 v112, 1.0, v112
	v_add_f32_e32 v113, 1.0, v113
	v_add_f32_e32 v114, 1.0, v114
	v_add_f32_e32 v115, 1.0, v115
	v_rcp_f32_e32 v108, v108
	v_rcp_f32_e32 v109, v109
	v_rcp_f32_e32 v110, v110
	v_rcp_f32_e32 v111, v111
	v_rcp_f32_e32 v112, v112
	v_rcp_f32_e32 v113, v113
	v_rcp_f32_e32 v114, v114
	v_rcp_f32_e32 v115, v115
	v_mul_f32_e32 v108, v84, v108
	v_mul_f32_e32 v109, v80, v109
	v_mul_f32_e32 v110, v85, v110
	v_mul_f32_e32 v111, v81, v111
	v_mul_f32_e32 v112, v86, v112
	v_mul_f32_e32 v113, v82, v113
	v_mul_f32_e32 v114, v87, v114
	v_mul_f32_e32 v115, v83, v115
	s_andn2_b64 vcc, exec, s[84:85]
	v_cvt_pk_bf16_f32 v116, v108, v110
	v_cvt_pk_bf16_f32 v117, v112, v114
	v_cvt_pk_bf16_f32 v118, v109, v111
	v_cvt_pk_bf16_f32 v119, v113, v115
	global_store_dwordx4 v[120:121], v[116:119], off offset:256
	s_cbranch_vccnz .LBB0_587
	s_nop 0
	v_mul_f32_e32 v116, v98, v98
	v_mul_f32_e32 v117, v106, v106
	v_fmac_f32_e32 v116, v96, v96
	v_fmac_f32_e32 v117, v104, v104
	v_add_f32_e32 v116, v116, v117
	v_mul_f32_e32 v117, v99, v99
	v_mul_f32_e32 v118, v107, v107
	v_fmac_f32_e32 v117, v97, v97
	v_fmac_f32_e32 v118, v105, v105
	v_add_f32_e32 v96, v96, v98
	v_add_f32_e32 v98, v104, v106
	v_add_f32_e32 v117, v117, v118
	v_add_f32_e32 v96, v96, v98
	v_add_f32_e32 v97, v97, v99
	v_add_f32_e32 v98, v105, v107
	v_add_f32_e32 v116, v116, v117
	v_mul_f32_e32 v117, v110, v110
	v_mul_f32_e32 v118, v114, v114
	v_add_f32_e32 v97, v97, v98
	v_fmac_f32_e32 v117, v108, v108
	v_fmac_f32_e32 v118, v112, v112
	v_add_f32_e32 v96, v96, v97
	v_add_f32_e32 v97, v108, v110
	v_add_f32_e32 v98, v112, v114
	v_add_f32_e32 v117, v117, v118
	v_mul_f32_e32 v118, v111, v111
	v_mul_f32_e32 v119, v115, v115
	v_add_f32_e32 v97, v97, v98
	v_add_f32_e32 v98, v109, v111
	v_add_f32_e32 v99, v113, v115
	v_fmac_f32_e32 v118, v109, v109
	v_fmac_f32_e32 v119, v113, v113
	v_add_f32_e32 v98, v98, v99
	v_add_f32_e32 v97, v97, v98
	v_add_f32_e32 v98, v118, v119
	v_add_f32_e32 v96, 0, v96
	v_add_f32_e32 v98, v117, v98
	v_add_f32_e32 v96, v96, v97
	v_add_f32_e32 v99, v116, v98
	ds_swizzle_b32 v97, v96 offset:swizzle(SWAP,16)
	ds_swizzle_b32 v104, v99 offset:swizzle(SWAP,16)
	s_waitcnt lgkmcnt(0)
	v_add_f32_e32 v96, v96, v97
	v_add_f32_e32 v97, v99, v104
	v_mov_b32_e32 v98, v96
	v_mov_b32_e32 v99, v97
	s_nop 0
	v_permlane32_swap_b32_e32 v96, v98
	v_permlane32_swap_b32_e32 v97, v99
	s_and_saveexec_b64 s[90:91], s[4:5]
	s_cbranch_execz .LBB0_586
	v_pk_add_f32 v[96:97], v[96:97], v[98:99]
	v_lshlrev_b64 v[98:99], 6, v[100:101]
	v_lshl_add_u64 v[98:99], s[18:19], 0, v[98:99]
	v_lshl_add_u64 v[98:99], s[52:53], 3, v[98:99]
	s_lshl_b32 s8, s40, 3
	s_mov_b32 s9, s53
	v_lshl_add_u64 v[98:99], v[98:99], 0, s[8:9]
	global_store_dwordx2 v[98:99], v[96:97], off

.LBB0_605:
	s_andn2_b64 vcc, exec, s[88:89]
	s_cbranch_vccnz .LBB0_610
	v_mul_f32_e32 v80, v76, v76
	v_mul_f32_e32 v81, v72, v72
	v_mul_f32_e32 v82, v77, v77
	v_mul_f32_e32 v83, v73, v73
	v_mul_f32_e32 v88, v78, v78
	v_mul_f32_e32 v89, v74, v74
	v_mul_f32_e32 v90, v79, v79
	v_mul_f32_e32 v91, v75, v75
	v_fmaak_f32 v80, v255, v80, 0xc0135761
	v_fmaak_f32 v81, v255, v81, 0xc0135761
	v_fmaak_f32 v82, v255, v82, 0xc0135761
	v_fmaak_f32 v83, v255, v83, 0xc0135761
	v_fmaak_f32 v88, v255, v88, 0xc0135761
	v_fmaak_f32 v89, v255, v89, 0xc0135761
	v_fmaak_f32 v90, v255, v90, 0xc0135761
	v_fmaak_f32 v91, v255, v91, 0xc0135761
	v_mul_f32_e32 v80, v76, v80
	v_mul_f32_e32 v81, v72, v81
	v_mul_f32_e32 v82, v77, v82
	v_mul_f32_e32 v83, v73, v83
	v_mul_f32_e32 v88, v78, v88
	v_mul_f32_e32 v89, v74, v89
	v_mul_f32_e32 v90, v79, v90
	v_mul_f32_e32 v91, v75, v91
	v_exp_f32_e32 v80, v80
	v_exp_f32_e32 v81, v81
	v_exp_f32_e32 v82, v82
	v_exp_f32_e32 v83, v83
	v_exp_f32_e32 v88, v88
	v_exp_f32_e32 v89, v89
	v_exp_f32_e32 v90, v90
	v_exp_f32_e32 v91, v91
	v_add_f32_e32 v80, 1.0, v80
	v_add_f32_e32 v81, 1.0, v81
	v_add_f32_e32 v82, 1.0, v82
	v_add_f32_e32 v83, 1.0, v83
	v_add_f32_e32 v88, 1.0, v88
	v_add_f32_e32 v89, 1.0, v89
	v_add_f32_e32 v90, 1.0, v90
	v_add_f32_e32 v91, 1.0, v91
	v_rcp_f32_e32 v80, v80
	v_rcp_f32_e32 v81, v81
	v_rcp_f32_e32 v82, v82
	v_rcp_f32_e32 v83, v83
	v_rcp_f32_e32 v88, v88
	v_rcp_f32_e32 v89, v89
	v_rcp_f32_e32 v90, v90
	v_rcp_f32_e32 v91, v91
	v_mul_f32_e32 v80, v76, v80
	v_mul_f32_e32 v81, v72, v81
	v_mul_f32_e32 v82, v77, v82
	v_mul_f32_e32 v83, v73, v83
	v_mul_f32_e32 v88, v78, v88
	v_mul_f32_e32 v89, v74, v89
	v_mul_f32_e32 v90, v79, v90
	v_mul_f32_e32 v91, v75, v91
	v_cvt_pk_bf16_f32 v92, v80, v82
	v_cvt_pk_bf16_f32 v93, v88, v90
	v_cvt_pk_bf16_f32 v94, v81, v83
	v_cvt_pk_bf16_f32 v95, v89, v91
	v_lshl_add_u64 v[104:105], v[148:149], 1, v[86:87]
	global_store_dwordx4 v[104:105], v[92:95], off
	v_mul_f32_e32 v96, v70, v70
	v_mul_f32_e32 v97, v66, v66
	v_mul_f32_e32 v92, v68, v68
	v_mul_f32_e32 v93, v64, v64
	v_mul_f32_e32 v94, v69, v69
	v_mul_f32_e32 v95, v65, v65
	v_mul_f32_e32 v98, v71, v71
	v_mul_f32_e32 v99, v67, v67
	v_fmaak_f32 v92, v255, v92, 0xc0135761
	v_fmaak_f32 v93, v255, v93, 0xc0135761
	v_fmaak_f32 v94, v255, v94, 0xc0135761
	v_fmaak_f32 v95, v255, v95, 0xc0135761
	v_fmaak_f32 v96, v255, v96, 0xc0135761
	v_fmaak_f32 v97, v255, v97, 0xc0135761
	v_fmaak_f32 v98, v255, v98, 0xc0135761
	v_fmaak_f32 v99, v255, v99, 0xc0135761
	v_mul_f32_e32 v92, v68, v92
	v_mul_f32_e32 v93, v64, v93
	v_mul_f32_e32 v94, v69, v94
	v_mul_f32_e32 v95, v65, v95
	v_mul_f32_e32 v96, v70, v96
	v_mul_f32_e32 v97, v66, v97
	v_mul_f32_e32 v98, v71, v98
	v_mul_f32_e32 v99, v67, v99
	v_exp_f32_e32 v92, v92
	v_exp_f32_e32 v93, v93
	v_exp_f32_e32 v94, v94
	v_exp_f32_e32 v95, v95
	v_exp_f32_e32 v96, v96
	v_exp_f32_e32 v97, v97
	v_exp_f32_e32 v98, v98
	v_exp_f32_e32 v99, v99
	v_add_f32_e32 v92, 1.0, v92
	v_add_f32_e32 v93, 1.0, v93
	v_add_f32_e32 v94, 1.0, v94
	v_add_f32_e32 v95, 1.0, v95
	v_add_f32_e32 v96, 1.0, v96
	v_add_f32_e32 v97, 1.0, v97
	v_add_f32_e32 v98, 1.0, v98
	v_add_f32_e32 v99, 1.0, v99
	v_rcp_f32_e32 v92, v92
	v_rcp_f32_e32 v93, v93
	v_rcp_f32_e32 v94, v94
	v_rcp_f32_e32 v95, v95
	v_rcp_f32_e32 v96, v96
	v_rcp_f32_e32 v97, v97
	v_rcp_f32_e32 v98, v98
	v_rcp_f32_e32 v99, v99
	v_mul_f32_e32 v92, v68, v92
	v_mul_f32_e32 v93, v64, v93
	v_mul_f32_e32 v94, v69, v94
	v_mul_f32_e32 v95, v65, v95
	v_mul_f32_e32 v96, v70, v96
	v_mul_f32_e32 v97, v66, v97
	v_mul_f32_e32 v98, v71, v98
	v_mul_f32_e32 v99, v67, v99
	s_andn2_b64 vcc, exec, s[84:85]
	v_cvt_pk_bf16_f32 v100, v92, v94
	v_cvt_pk_bf16_f32 v101, v96, v98
	v_cvt_pk_bf16_f32 v102, v93, v95
	v_cvt_pk_bf16_f32 v103, v97, v99
	global_store_dwordx4 v[104:105], v[100:103], off offset:256
	s_cbranch_vccnz .LBB0_610
	s_nop 0
	v_mul_f32_e32 v100, v82, v82
	v_mul_f32_e32 v101, v90, v90
	v_fmac_f32_e32 v100, v80, v80
	v_fmac_f32_e32 v101, v88, v88
	v_add_f32_e32 v100, v100, v101
	v_mul_f32_e32 v101, v83, v83
	v_mul_f32_e32 v102, v91, v91
	v_fmac_f32_e32 v101, v81, v81
	v_fmac_f32_e32 v102, v89, v89
	v_add_f32_e32 v80, v80, v82
	v_add_f32_e32 v82, v88, v90
	v_add_f32_e32 v101, v101, v102
	v_add_f32_e32 v80, v80, v82
	v_add_f32_e32 v81, v81, v83
	v_add_f32_e32 v82, v89, v91
	v_add_f32_e32 v100, v100, v101
	v_mul_f32_e32 v101, v94, v94
	v_mul_f32_e32 v102, v98, v98
	v_add_f32_e32 v81, v81, v82
	v_fmac_f32_e32 v101, v92, v92
	v_fmac_f32_e32 v102, v96, v96
	v_add_f32_e32 v80, v80, v81
	v_add_f32_e32 v81, v92, v94
	v_add_f32_e32 v82, v96, v98
	v_add_f32_e32 v101, v101, v102
	v_mul_f32_e32 v102, v95, v95
	v_mul_f32_e32 v103, v99, v99
	v_add_f32_e32 v81, v81, v82
	v_add_f32_e32 v82, v93, v95
	v_add_f32_e32 v83, v97, v99
	v_fmac_f32_e32 v102, v93, v93
	v_fmac_f32_e32 v103, v97, v97
	v_add_f32_e32 v82, v82, v83
	v_add_f32_e32 v81, v81, v82
	v_add_f32_e32 v82, v102, v103
	v_add_f32_e32 v80, 0, v80
	v_add_f32_e32 v82, v101, v82
	v_add_f32_e32 v80, v80, v81
	v_add_f32_e32 v83, v100, v82
	ds_swizzle_b32 v81, v80 offset:swizzle(SWAP,16)
	ds_swizzle_b32 v88, v83 offset:swizzle(SWAP,16)
	s_waitcnt lgkmcnt(0)
	v_add_f32_e32 v80, v80, v81
	v_add_f32_e32 v81, v83, v88
	v_mov_b32_e32 v82, v80
	v_mov_b32_e32 v83, v81
	s_nop 0
	v_permlane32_swap_b32_e32 v80, v82
	v_permlane32_swap_b32_e32 v81, v83
	s_and_saveexec_b64 s[88:89], s[4:5]
	s_cbranch_execz .LBB0_609
	v_pk_add_f32 v[80:81], v[80:81], v[82:83]
	v_lshlrev_b64 v[82:83], 6, v[84:85]
	v_lshl_add_u64 v[82:83], s[18:19], 0, v[82:83]
	v_lshl_add_u64 v[82:83], s[52:53], 3, v[82:83]
	s_lshl_b32 s8, s40, 3
	s_mov_b32 s9, s53
	v_lshl_add_u64 v[82:83], v[82:83], 0, s[8:9]
	global_store_dwordx2 v[82:83], v[80:81], off

.LBB0_628:
	s_andn2_b64 vcc, exec, s[90:91]
	s_cbranch_vccnz .LBB0_633
	v_mul_f32_e32 v64, v60, v60
	v_mul_f32_e32 v65, v56, v56
	v_mul_f32_e32 v66, v61, v61
	v_mul_f32_e32 v67, v57, v57
	v_mul_f32_e32 v72, v62, v62
	v_mul_f32_e32 v73, v58, v58
	v_mul_f32_e32 v74, v63, v63
	v_mul_f32_e32 v75, v59, v59
	v_fmaak_f32 v64, v255, v64, 0xc0135761
	v_fmaak_f32 v65, v255, v65, 0xc0135761
	v_fmaak_f32 v66, v255, v66, 0xc0135761
	v_fmaak_f32 v67, v255, v67, 0xc0135761
	v_fmaak_f32 v72, v255, v72, 0xc0135761
	v_fmaak_f32 v73, v255, v73, 0xc0135761
	v_fmaak_f32 v74, v255, v74, 0xc0135761
	v_fmaak_f32 v75, v255, v75, 0xc0135761
	v_mul_f32_e32 v64, v60, v64
	v_mul_f32_e32 v65, v56, v65
	v_mul_f32_e32 v66, v61, v66
	v_mul_f32_e32 v67, v57, v67
	v_mul_f32_e32 v72, v62, v72
	v_mul_f32_e32 v73, v58, v73
	v_mul_f32_e32 v74, v63, v74
	v_mul_f32_e32 v75, v59, v75
	v_exp_f32_e32 v64, v64
	v_exp_f32_e32 v65, v65
	v_exp_f32_e32 v66, v66
	v_exp_f32_e32 v67, v67
	v_exp_f32_e32 v72, v72
	v_exp_f32_e32 v73, v73
	v_exp_f32_e32 v74, v74
	v_exp_f32_e32 v75, v75
	v_add_f32_e32 v64, 1.0, v64
	v_add_f32_e32 v65, 1.0, v65
	v_add_f32_e32 v66, 1.0, v66
	v_add_f32_e32 v67, 1.0, v67
	v_add_f32_e32 v72, 1.0, v72
	v_add_f32_e32 v73, 1.0, v73
	v_add_f32_e32 v74, 1.0, v74
	v_add_f32_e32 v75, 1.0, v75
	v_rcp_f32_e32 v64, v64
	v_rcp_f32_e32 v65, v65
	v_rcp_f32_e32 v66, v66
	v_rcp_f32_e32 v67, v67
	v_rcp_f32_e32 v72, v72
	v_rcp_f32_e32 v73, v73
	v_rcp_f32_e32 v74, v74
	v_rcp_f32_e32 v75, v75
	v_mul_f32_e32 v64, v60, v64
	v_mul_f32_e32 v65, v56, v65
	v_mul_f32_e32 v66, v61, v66
	v_mul_f32_e32 v67, v57, v67
	v_mul_f32_e32 v72, v62, v72
	v_mul_f32_e32 v73, v58, v73
	v_mul_f32_e32 v74, v63, v74
	v_mul_f32_e32 v75, v59, v75
	v_cvt_pk_bf16_f32 v76, v64, v66
	v_cvt_pk_bf16_f32 v77, v72, v74
	v_cvt_pk_bf16_f32 v78, v65, v67
	v_cvt_pk_bf16_f32 v79, v73, v75
	v_lshl_add_u64 v[88:89], v[148:149], 1, v[70:71]
	global_store_dwordx4 v[88:89], v[76:79], off
	v_mul_f32_e32 v80, v54, v54
	v_mul_f32_e32 v81, v50, v50
	v_mul_f32_e32 v76, v52, v52
	v_mul_f32_e32 v77, v48, v48
	v_mul_f32_e32 v78, v53, v53
	v_mul_f32_e32 v79, v49, v49
	v_mul_f32_e32 v82, v55, v55
	v_mul_f32_e32 v83, v51, v51
	v_fmaak_f32 v76, v255, v76, 0xc0135761
	v_fmaak_f32 v77, v255, v77, 0xc0135761
	v_fmaak_f32 v78, v255, v78, 0xc0135761
	v_fmaak_f32 v79, v255, v79, 0xc0135761
	v_fmaak_f32 v80, v255, v80, 0xc0135761
	v_fmaak_f32 v81, v255, v81, 0xc0135761
	v_fmaak_f32 v82, v255, v82, 0xc0135761
	v_fmaak_f32 v83, v255, v83, 0xc0135761
	v_mul_f32_e32 v76, v52, v76
	v_mul_f32_e32 v77, v48, v77
	v_mul_f32_e32 v78, v53, v78
	v_mul_f32_e32 v79, v49, v79
	v_mul_f32_e32 v80, v54, v80
	v_mul_f32_e32 v81, v50, v81
	v_mul_f32_e32 v82, v55, v82
	v_mul_f32_e32 v83, v51, v83
	v_exp_f32_e32 v76, v76
	v_exp_f32_e32 v77, v77
	v_exp_f32_e32 v78, v78
	v_exp_f32_e32 v79, v79
	v_exp_f32_e32 v80, v80
	v_exp_f32_e32 v81, v81
	v_exp_f32_e32 v82, v82
	v_exp_f32_e32 v83, v83
	v_add_f32_e32 v76, 1.0, v76
	v_add_f32_e32 v77, 1.0, v77
	v_add_f32_e32 v78, 1.0, v78
	v_add_f32_e32 v79, 1.0, v79
	v_add_f32_e32 v80, 1.0, v80
	v_add_f32_e32 v81, 1.0, v81
	v_add_f32_e32 v82, 1.0, v82
	v_add_f32_e32 v83, 1.0, v83
	v_rcp_f32_e32 v76, v76
	v_rcp_f32_e32 v77, v77
	v_rcp_f32_e32 v78, v78
	v_rcp_f32_e32 v79, v79
	v_rcp_f32_e32 v80, v80
	v_rcp_f32_e32 v81, v81
	v_rcp_f32_e32 v82, v82
	v_rcp_f32_e32 v83, v83
	v_mul_f32_e32 v76, v52, v76
	v_mul_f32_e32 v77, v48, v77
	v_mul_f32_e32 v78, v53, v78
	v_mul_f32_e32 v79, v49, v79
	v_mul_f32_e32 v80, v54, v80
	v_mul_f32_e32 v81, v50, v81
	v_mul_f32_e32 v82, v55, v82
	v_mul_f32_e32 v83, v51, v83
	s_andn2_b64 vcc, exec, s[84:85]
	v_cvt_pk_bf16_f32 v84, v76, v78
	v_cvt_pk_bf16_f32 v85, v80, v82
	v_cvt_pk_bf16_f32 v86, v77, v79
	v_cvt_pk_bf16_f32 v87, v81, v83
	global_store_dwordx4 v[88:89], v[84:87], off offset:256
	s_cbranch_vccnz .LBB0_633
	s_nop 0
	v_mul_f32_e32 v84, v66, v66
	v_mul_f32_e32 v85, v74, v74
	v_fmac_f32_e32 v84, v64, v64
	v_fmac_f32_e32 v85, v72, v72
	v_add_f32_e32 v84, v84, v85
	v_mul_f32_e32 v85, v67, v67
	v_mul_f32_e32 v86, v75, v75
	v_fmac_f32_e32 v85, v65, v65
	v_fmac_f32_e32 v86, v73, v73
	v_add_f32_e32 v64, v64, v66
	v_add_f32_e32 v66, v72, v74
	v_add_f32_e32 v85, v85, v86
	v_add_f32_e32 v64, v64, v66
	v_add_f32_e32 v65, v65, v67
	v_add_f32_e32 v66, v73, v75
	v_add_f32_e32 v84, v84, v85
	v_mul_f32_e32 v85, v78, v78
	v_mul_f32_e32 v86, v82, v82
	v_add_f32_e32 v65, v65, v66
	v_fmac_f32_e32 v85, v76, v76
	v_fmac_f32_e32 v86, v80, v80
	v_add_f32_e32 v64, v64, v65
	v_add_f32_e32 v65, v76, v78
	v_add_f32_e32 v66, v80, v82
	v_add_f32_e32 v85, v85, v86
	v_mul_f32_e32 v86, v79, v79
	v_mul_f32_e32 v87, v83, v83
	v_add_f32_e32 v65, v65, v66
	v_add_f32_e32 v66, v77, v79
	v_add_f32_e32 v67, v81, v83
	v_fmac_f32_e32 v86, v77, v77
	v_fmac_f32_e32 v87, v81, v81
	v_add_f32_e32 v66, v66, v67
	v_add_f32_e32 v65, v65, v66
	v_add_f32_e32 v66, v86, v87
	v_add_f32_e32 v64, 0, v64
	v_add_f32_e32 v66, v85, v66
	v_add_f32_e32 v64, v64, v65
	v_add_f32_e32 v67, v84, v66
	ds_swizzle_b32 v65, v64 offset:swizzle(SWAP,16)
	ds_swizzle_b32 v72, v67 offset:swizzle(SWAP,16)
	s_waitcnt lgkmcnt(0)
	v_add_f32_e32 v64, v64, v65
	v_add_f32_e32 v65, v67, v72
	v_mov_b32_e32 v66, v64
	v_mov_b32_e32 v67, v65
	s_nop 0
	v_permlane32_swap_b32_e32 v64, v66
	v_permlane32_swap_b32_e32 v65, v67
	s_and_saveexec_b64 s[90:91], s[4:5]
	s_cbranch_execz .LBB0_632
	v_pk_add_f32 v[64:65], v[64:65], v[66:67]
	v_lshlrev_b64 v[66:67], 6, v[68:69]
	v_lshl_add_u64 v[66:67], s[18:19], 0, v[66:67]
	v_lshl_add_u64 v[66:67], s[52:53], 3, v[66:67]
	s_lshl_b32 s8, s40, 3
	s_mov_b32 s9, s53
	v_lshl_add_u64 v[66:67], v[66:67], 0, s[8:9]
	global_store_dwordx2 v[66:67], v[64:65], off

.LBB0_651:
	s_andn2_b64 vcc, exec, s[90:91]
	s_cbranch_vccnz .LBB0_656
	v_mul_f32_e32 v48, v44, v44
	v_mul_f32_e32 v49, v40, v40
	v_mul_f32_e32 v50, v45, v45
	v_mul_f32_e32 v51, v41, v41
	v_mul_f32_e32 v56, v46, v46
	v_mul_f32_e32 v57, v42, v42
	v_mul_f32_e32 v58, v47, v47
	v_mul_f32_e32 v59, v43, v43
	v_fmaak_f32 v48, v255, v48, 0xc0135761
	v_fmaak_f32 v49, v255, v49, 0xc0135761
	v_fmaak_f32 v50, v255, v50, 0xc0135761
	v_fmaak_f32 v51, v255, v51, 0xc0135761
	v_fmaak_f32 v56, v255, v56, 0xc0135761
	v_fmaak_f32 v57, v255, v57, 0xc0135761
	v_fmaak_f32 v58, v255, v58, 0xc0135761
	v_fmaak_f32 v59, v255, v59, 0xc0135761
	v_mul_f32_e32 v48, v44, v48
	v_mul_f32_e32 v49, v40, v49
	v_mul_f32_e32 v50, v45, v50
	v_mul_f32_e32 v51, v41, v51
	v_mul_f32_e32 v56, v46, v56
	v_mul_f32_e32 v57, v42, v57
	v_mul_f32_e32 v58, v47, v58
	v_mul_f32_e32 v59, v43, v59
	v_exp_f32_e32 v48, v48
	v_exp_f32_e32 v49, v49
	v_exp_f32_e32 v50, v50
	v_exp_f32_e32 v51, v51
	v_exp_f32_e32 v56, v56
	v_exp_f32_e32 v57, v57
	v_exp_f32_e32 v58, v58
	v_exp_f32_e32 v59, v59
	v_add_f32_e32 v48, 1.0, v48
	v_add_f32_e32 v49, 1.0, v49
	v_add_f32_e32 v50, 1.0, v50
	v_add_f32_e32 v51, 1.0, v51
	v_add_f32_e32 v56, 1.0, v56
	v_add_f32_e32 v57, 1.0, v57
	v_add_f32_e32 v58, 1.0, v58
	v_add_f32_e32 v59, 1.0, v59
	v_rcp_f32_e32 v48, v48
	v_rcp_f32_e32 v49, v49
	v_rcp_f32_e32 v50, v50
	v_rcp_f32_e32 v51, v51
	v_rcp_f32_e32 v56, v56
	v_rcp_f32_e32 v57, v57
	v_rcp_f32_e32 v58, v58
	v_rcp_f32_e32 v59, v59
	v_mul_f32_e32 v48, v44, v48
	v_mul_f32_e32 v49, v40, v49
	v_mul_f32_e32 v50, v45, v50
	v_mul_f32_e32 v51, v41, v51
	v_mul_f32_e32 v56, v46, v56
	v_mul_f32_e32 v57, v42, v57
	v_mul_f32_e32 v58, v47, v58
	v_mul_f32_e32 v59, v43, v59
	v_cvt_pk_bf16_f32 v60, v48, v50
	v_cvt_pk_bf16_f32 v61, v56, v58
	v_cvt_pk_bf16_f32 v62, v49, v51
	v_cvt_pk_bf16_f32 v63, v57, v59
	v_lshl_add_u64 v[74:75], v[148:149], 1, v[54:55]
	global_store_dwordx4 v[74:75], v[60:63], off
	v_mul_f32_e32 v64, v38, v38
	v_mul_f32_e32 v65, v34, v34
	v_mul_f32_e32 v60, v36, v36
	v_mul_f32_e32 v61, v32, v32
	v_mul_f32_e32 v62, v37, v37
	v_mul_f32_e32 v63, v33, v33
	v_mul_f32_e32 v66, v39, v39
	v_mul_f32_e32 v67, v35, v35
	v_fmaak_f32 v60, v255, v60, 0xc0135761
	v_fmaak_f32 v61, v255, v61, 0xc0135761
	v_fmaak_f32 v62, v255, v62, 0xc0135761
	v_fmaak_f32 v63, v255, v63, 0xc0135761
	v_fmaak_f32 v64, v255, v64, 0xc0135761
	v_fmaak_f32 v65, v255, v65, 0xc0135761
	v_fmaak_f32 v66, v255, v66, 0xc0135761
	v_fmaak_f32 v67, v255, v67, 0xc0135761
	v_mul_f32_e32 v60, v36, v60
	v_mul_f32_e32 v61, v32, v61
	v_mul_f32_e32 v62, v37, v62
	v_mul_f32_e32 v63, v33, v63
	v_mul_f32_e32 v64, v38, v64
	v_mul_f32_e32 v65, v34, v65
	v_mul_f32_e32 v66, v39, v66
	v_mul_f32_e32 v67, v35, v67
	v_exp_f32_e32 v60, v60
	v_exp_f32_e32 v61, v61
	v_exp_f32_e32 v62, v62
	v_exp_f32_e32 v63, v63
	v_exp_f32_e32 v64, v64
	v_exp_f32_e32 v65, v65
	v_exp_f32_e32 v66, v66
	v_exp_f32_e32 v67, v67
	v_add_f32_e32 v60, 1.0, v60
	v_add_f32_e32 v61, 1.0, v61
	v_add_f32_e32 v62, 1.0, v62
	v_add_f32_e32 v63, 1.0, v63
	v_add_f32_e32 v64, 1.0, v64
	v_add_f32_e32 v65, 1.0, v65
	v_add_f32_e32 v66, 1.0, v66
	v_add_f32_e32 v67, 1.0, v67
	v_rcp_f32_e32 v60, v60
	v_rcp_f32_e32 v61, v61
	v_rcp_f32_e32 v62, v62
	v_rcp_f32_e32 v63, v63
	v_rcp_f32_e32 v64, v64
	v_rcp_f32_e32 v65, v65
	v_rcp_f32_e32 v66, v66
	v_rcp_f32_e32 v67, v67
	v_mul_f32_e32 v60, v36, v60
	v_mul_f32_e32 v61, v32, v61
	v_mul_f32_e32 v62, v37, v62
	v_mul_f32_e32 v63, v33, v63
	v_mul_f32_e32 v64, v38, v64
	v_mul_f32_e32 v65, v34, v65
	v_mul_f32_e32 v66, v39, v66
	v_mul_f32_e32 v67, v35, v67
	s_andn2_b64 vcc, exec, s[84:85]
	v_cvt_pk_bf16_f32 v70, v60, v62
	v_cvt_pk_bf16_f32 v71, v64, v66
	v_cvt_pk_bf16_f32 v72, v61, v63
	v_cvt_pk_bf16_f32 v73, v65, v67
	global_store_dwordx4 v[74:75], v[70:73], off offset:256
	s_cbranch_vccnz .LBB0_656
	v_mul_f32_e32 v69, v50, v50
	v_mul_f32_e32 v70, v58, v58
	v_fmac_f32_e32 v69, v48, v48
	v_fmac_f32_e32 v70, v56, v56
	v_add_f32_e32 v69, v69, v70
	v_mul_f32_e32 v70, v51, v51
	v_mul_f32_e32 v71, v59, v59
	v_fmac_f32_e32 v70, v49, v49
	v_fmac_f32_e32 v71, v57, v57
	v_add_f32_e32 v48, v48, v50
	v_add_f32_e32 v50, v56, v58
	v_add_f32_e32 v70, v70, v71
	v_add_f32_e32 v48, v48, v50
	v_add_f32_e32 v49, v49, v51
	v_add_f32_e32 v50, v57, v59
	v_add_f32_e32 v69, v69, v70
	v_mul_f32_e32 v70, v62, v62
	v_mul_f32_e32 v71, v66, v66
	v_add_f32_e32 v49, v49, v50
	v_fmac_f32_e32 v70, v60, v60
	v_fmac_f32_e32 v71, v64, v64
	v_add_f32_e32 v48, v48, v49
	v_add_f32_e32 v49, v60, v62
	v_add_f32_e32 v50, v64, v66
	v_add_f32_e32 v70, v70, v71
	v_mul_f32_e32 v71, v63, v63
	v_mul_f32_e32 v72, v67, v67
	v_add_f32_e32 v49, v49, v50
	v_add_f32_e32 v50, v61, v63
	v_add_f32_e32 v51, v65, v67
	v_fmac_f32_e32 v71, v61, v61
	v_fmac_f32_e32 v72, v65, v65
	v_add_f32_e32 v50, v50, v51
	v_add_f32_e32 v49, v49, v50
	v_add_f32_e32 v50, v71, v72
	v_add_f32_e32 v48, 0, v48
	v_add_f32_e32 v50, v70, v50
	v_add_f32_e32 v48, v48, v49
	v_add_f32_e32 v51, v69, v50
	ds_swizzle_b32 v49, v48 offset:swizzle(SWAP,16)
	ds_swizzle_b32 v56, v51 offset:swizzle(SWAP,16)
	s_waitcnt lgkmcnt(0)
	v_add_f32_e32 v48, v48, v49
	v_add_f32_e32 v49, v51, v56
	v_mov_b32_e32 v50, v48
	v_mov_b32_e32 v51, v49
	s_nop 0
	v_permlane32_swap_b32_e32 v48, v50
	v_permlane32_swap_b32_e32 v49, v51
	s_and_saveexec_b64 s[90:91], s[4:5]
	s_cbranch_execz .LBB0_655
	v_pk_add_f32 v[48:49], v[48:49], v[50:51]
	v_lshlrev_b64 v[50:51], 6, v[52:53]
	v_lshl_add_u64 v[50:51], s[18:19], 0, v[50:51]
	v_lshl_add_u64 v[50:51], s[52:53], 3, v[50:51]
	s_lshl_b32 s8, s40, 3
	s_mov_b32 s9, s53
	v_lshl_add_u64 v[50:51], v[50:51], 0, s[8:9]
	global_store_dwordx2 v[50:51], v[48:49], off

.LBB0_674:
	s_andn2_b64 vcc, exec, s[90:91]
	s_cbranch_vccnz .LBB0_679
	v_mul_f32_e32 v32, v28, v28
	v_mul_f32_e32 v33, v24, v24
	v_mul_f32_e32 v34, v29, v29
	v_mul_f32_e32 v35, v25, v25
	v_mul_f32_e32 v40, v30, v30
	v_mul_f32_e32 v41, v26, v26
	v_mul_f32_e32 v42, v31, v31
	v_mul_f32_e32 v43, v27, v27
	v_fmaak_f32 v32, v255, v32, 0xc0135761
	v_fmaak_f32 v33, v255, v33, 0xc0135761
	v_fmaak_f32 v34, v255, v34, 0xc0135761
	v_fmaak_f32 v35, v255, v35, 0xc0135761
	v_fmaak_f32 v40, v255, v40, 0xc0135761
	v_fmaak_f32 v41, v255, v41, 0xc0135761
	v_fmaak_f32 v42, v255, v42, 0xc0135761
	v_fmaak_f32 v43, v255, v43, 0xc0135761
	v_mul_f32_e32 v32, v28, v32
	v_mul_f32_e32 v33, v24, v33
	v_mul_f32_e32 v34, v29, v34
	v_mul_f32_e32 v35, v25, v35
	v_mul_f32_e32 v40, v30, v40
	v_mul_f32_e32 v41, v26, v41
	v_mul_f32_e32 v42, v31, v42
	v_mul_f32_e32 v43, v27, v43
	v_exp_f32_e32 v32, v32
	v_exp_f32_e32 v33, v33
	v_exp_f32_e32 v34, v34
	v_exp_f32_e32 v35, v35
	v_exp_f32_e32 v40, v40
	v_exp_f32_e32 v41, v41
	v_exp_f32_e32 v42, v42
	v_exp_f32_e32 v43, v43
	v_add_f32_e32 v32, 1.0, v32
	v_add_f32_e32 v33, 1.0, v33
	v_add_f32_e32 v34, 1.0, v34
	v_add_f32_e32 v35, 1.0, v35
	v_add_f32_e32 v40, 1.0, v40
	v_add_f32_e32 v41, 1.0, v41
	v_add_f32_e32 v42, 1.0, v42
	v_add_f32_e32 v43, 1.0, v43
	v_rcp_f32_e32 v32, v32
	v_rcp_f32_e32 v33, v33
	v_rcp_f32_e32 v34, v34
	v_rcp_f32_e32 v35, v35
	v_rcp_f32_e32 v40, v40
	v_rcp_f32_e32 v41, v41
	v_rcp_f32_e32 v42, v42
	v_rcp_f32_e32 v43, v43
	v_mul_f32_e32 v32, v28, v32
	v_mul_f32_e32 v33, v24, v33
	v_mul_f32_e32 v34, v29, v34
	v_mul_f32_e32 v35, v25, v35
	v_mul_f32_e32 v40, v30, v40
	v_mul_f32_e32 v41, v26, v41
	v_mul_f32_e32 v42, v31, v42
	v_mul_f32_e32 v43, v27, v43
	v_cvt_pk_bf16_f32 v44, v32, v34
	v_cvt_pk_bf16_f32 v45, v40, v42
	v_cvt_pk_bf16_f32 v46, v33, v35
	v_cvt_pk_bf16_f32 v47, v41, v43
	v_lshl_add_u64 v[56:57], v[148:149], 1, v[38:39]
	global_store_dwordx4 v[56:57], v[44:47], off
	v_mul_f32_e32 v48, v22, v22
	v_mul_f32_e32 v49, v18, v18
	v_mul_f32_e32 v44, v20, v20
	v_mul_f32_e32 v45, v16, v16
	v_mul_f32_e32 v46, v21, v21
	v_mul_f32_e32 v47, v17, v17
	v_mul_f32_e32 v50, v23, v23
	v_mul_f32_e32 v51, v19, v19
	v_fmaak_f32 v44, v255, v44, 0xc0135761
	v_fmaak_f32 v45, v255, v45, 0xc0135761
	v_fmaak_f32 v46, v255, v46, 0xc0135761
	v_fmaak_f32 v47, v255, v47, 0xc0135761
	v_fmaak_f32 v48, v255, v48, 0xc0135761
	v_fmaak_f32 v49, v255, v49, 0xc0135761
	v_fmaak_f32 v50, v255, v50, 0xc0135761
	v_fmaak_f32 v51, v255, v51, 0xc0135761
	v_mul_f32_e32 v44, v20, v44
	v_mul_f32_e32 v45, v16, v45
	v_mul_f32_e32 v46, v21, v46
	v_mul_f32_e32 v47, v17, v47
	v_mul_f32_e32 v48, v22, v48
	v_mul_f32_e32 v49, v18, v49
	v_mul_f32_e32 v50, v23, v50
	v_mul_f32_e32 v51, v19, v51
	v_exp_f32_e32 v44, v44
	v_exp_f32_e32 v45, v45
	v_exp_f32_e32 v46, v46
	v_exp_f32_e32 v47, v47
	v_exp_f32_e32 v48, v48
	v_exp_f32_e32 v49, v49
	v_exp_f32_e32 v50, v50
	v_exp_f32_e32 v51, v51
	v_add_f32_e32 v44, 1.0, v44
	v_add_f32_e32 v45, 1.0, v45
	v_add_f32_e32 v46, 1.0, v46
	v_add_f32_e32 v47, 1.0, v47
	v_add_f32_e32 v48, 1.0, v48
	v_add_f32_e32 v49, 1.0, v49
	v_add_f32_e32 v50, 1.0, v50
	v_add_f32_e32 v51, 1.0, v51
	v_rcp_f32_e32 v44, v44
	v_rcp_f32_e32 v45, v45
	v_rcp_f32_e32 v46, v46
	v_rcp_f32_e32 v47, v47
	v_rcp_f32_e32 v48, v48
	v_rcp_f32_e32 v49, v49
	v_rcp_f32_e32 v50, v50
	v_rcp_f32_e32 v51, v51
	v_mul_f32_e32 v44, v20, v44
	v_mul_f32_e32 v45, v16, v45
	v_mul_f32_e32 v46, v21, v46
	v_mul_f32_e32 v47, v17, v47
	v_mul_f32_e32 v48, v22, v48
	v_mul_f32_e32 v49, v18, v49
	v_mul_f32_e32 v50, v23, v50
	v_mul_f32_e32 v51, v19, v51
	s_andn2_b64 vcc, exec, s[84:85]
	v_cvt_pk_bf16_f32 v52, v44, v46
	v_cvt_pk_bf16_f32 v53, v48, v50
	v_cvt_pk_bf16_f32 v54, v45, v47
	v_cvt_pk_bf16_f32 v55, v49, v51
	global_store_dwordx4 v[56:57], v[52:55], off offset:256
	s_cbranch_vccnz .LBB0_679
	s_nop 0
	v_mul_f32_e32 v52, v34, v34
	v_mul_f32_e32 v53, v42, v42
	v_fmac_f32_e32 v52, v32, v32
	v_fmac_f32_e32 v53, v40, v40
	v_add_f32_e32 v52, v52, v53
	v_mul_f32_e32 v53, v35, v35
	v_mul_f32_e32 v54, v43, v43
	v_fmac_f32_e32 v53, v33, v33
	v_fmac_f32_e32 v54, v41, v41
	v_add_f32_e32 v32, v32, v34
	v_add_f32_e32 v34, v40, v42
	v_add_f32_e32 v53, v53, v54
	v_add_f32_e32 v32, v32, v34
	v_add_f32_e32 v33, v33, v35
	v_add_f32_e32 v34, v41, v43
	v_add_f32_e32 v52, v52, v53
	v_mul_f32_e32 v53, v46, v46
	v_mul_f32_e32 v54, v50, v50
	v_add_f32_e32 v33, v33, v34
	v_fmac_f32_e32 v53, v44, v44
	v_fmac_f32_e32 v54, v48, v48
	v_add_f32_e32 v32, v32, v33
	v_add_f32_e32 v33, v44, v46
	v_add_f32_e32 v34, v48, v50
	v_add_f32_e32 v53, v53, v54
	v_mul_f32_e32 v54, v47, v47
	v_mul_f32_e32 v55, v51, v51
	v_add_f32_e32 v33, v33, v34
	v_add_f32_e32 v34, v45, v47
	v_add_f32_e32 v35, v49, v51
	v_fmac_f32_e32 v54, v45, v45
	v_fmac_f32_e32 v55, v49, v49
	v_add_f32_e32 v34, v34, v35
	v_add_f32_e32 v33, v33, v34
	v_add_f32_e32 v34, v54, v55
	v_add_f32_e32 v32, 0, v32
	v_add_f32_e32 v34, v53, v34
	v_add_f32_e32 v32, v32, v33
	v_add_f32_e32 v35, v52, v34
	ds_swizzle_b32 v33, v32 offset:swizzle(SWAP,16)
	ds_swizzle_b32 v40, v35 offset:swizzle(SWAP,16)
	s_waitcnt lgkmcnt(0)
	v_add_f32_e32 v32, v32, v33
	v_add_f32_e32 v33, v35, v40
	v_mov_b32_e32 v34, v32
	v_mov_b32_e32 v35, v33
	s_nop 0
	v_permlane32_swap_b32_e32 v32, v34
	v_permlane32_swap_b32_e32 v33, v35
	s_and_saveexec_b64 s[90:91], s[4:5]
	s_cbranch_execz .LBB0_678
	v_pk_add_f32 v[32:33], v[32:33], v[34:35]
	v_lshlrev_b64 v[34:35], 6, v[36:37]
	v_lshl_add_u64 v[34:35], s[18:19], 0, v[34:35]
	v_lshl_add_u64 v[34:35], s[52:53], 3, v[34:35]
	s_lshl_b32 s8, s40, 3
	s_mov_b32 s9, s53
	v_lshl_add_u64 v[34:35], v[34:35], 0, s[8:9]
	global_store_dwordx2 v[34:35], v[32:33], off

.LBB0_697:
	s_andn2_b64 vcc, exec, s[6:7]
	s_cbranch_vccnz .LBB0_702
	v_mul_f32_e32 v17, v8, v8
	v_fmaak_f32 v17, v255, v17, 0xc0135761
	v_mul_f32_e32 v18, v13, v13
	v_mul_f32_e32 v17, v8, v17
	v_fmaak_f32 v18, v255, v18, 0xc0135761
	v_mul_f32_e32 v18, v13, v18
	v_exp_f32_e32 v17, v17
	v_mul_f32_e32 v16, v12, v12
	v_exp_f32_e32 v18, v18
	v_fmaak_f32 v16, v255, v16, 0xc0135761
	v_mul_f32_e32 v16, v12, v16
	v_add_f32_e32 v17, 1.0, v17
	v_rcp_f32_e32 v19, v17
	v_add_f32_e32 v17, 1.0, v18
	v_exp_f32_e32 v16, v16
	v_rcp_f32_e32 v18, v17
	v_mul_f32_e32 v17, v9, v9
	v_fmaak_f32 v17, v255, v17, 0xc0135761
	v_mul_f32_e32 v17, v9, v17
	v_add_f32_e32 v16, 1.0, v16
	v_rcp_f32_e32 v16, v16
	v_exp_f32_e32 v24, v17
	v_mul_f32_e32 v25, v10, v10
	v_fmaak_f32 v25, v255, v25, 0xc0135761
	v_mul_f32_e32 v26, v15, v15
	v_mul_f32_e32 v17, v12, v16
	v_mul_f32_e32 v16, v8, v19
	v_add_f32_e32 v19, 1.0, v24
	v_mul_f32_e32 v24, v14, v14
	v_mul_f32_e32 v25, v10, v25
	v_fmaak_f32 v26, v255, v26, 0xc0135761
	v_mul_f32_e32 v27, v11, v11
	v_fmaak_f32 v24, v255, v24, 0xc0135761
	v_mul_f32_e32 v26, v15, v26
	v_fmaak_f32 v27, v255, v27, 0xc0135761
	v_mul_f32_e32 v24, v14, v24
	v_mul_f32_e32 v27, v11, v27
	v_exp_f32_e32 v25, v25
	v_exp_f32_e32 v26, v26
	v_exp_f32_e32 v24, v24
	v_exp_f32_e32 v27, v27
	v_add_f32_e32 v25, 1.0, v25
	v_rcp_f32_e32 v28, v25
	v_add_f32_e32 v25, 1.0, v26
	v_add_f32_e32 v24, 1.0, v24
	v_rcp_f32_e32 v26, v25
	v_add_f32_e32 v25, 1.0, v27
	v_rcp_f32_e32 v24, v24
	v_rcp_f32_e32 v29, v25
	v_mul_f32_e32 v31, v4, v4
	v_rcp_f32_e32 v19, v19
	v_fmaak_f32 v31, v255, v31, 0xc0135761
	v_mul_f32_e32 v31, v4, v31
	v_mul_f32_e32 v18, v13, v18
	v_mul_f32_e32 v25, v14, v24
	v_mul_f32_e32 v24, v10, v28
	v_mul_f32_e32 v27, v15, v26
	v_mul_f32_e32 v26, v11, v29
	v_cvt_pk_bf16_f32 v28, v17, v18
	v_cvt_pk_bf16_f32 v29, v25, v27
	v_lshl_add_u64 v[40:41], v[148:149], 1, v[22:23]
	v_mul_f32_e32 v19, v9, v19
	v_cvt_pk_bf16_f32 v30, v16, v19
	v_exp_f32_e32 v32, v31
	v_cvt_pk_bf16_f32 v31, v24, v26
	global_store_dwordx4 v[40:41], v[28:31], off
	v_mul_f32_e32 v33, v2, v2
	v_fmaak_f32 v33, v255, v33, 0xc0135761
	v_mul_f32_e32 v29, v0, v0
	v_fmaak_f32 v29, v255, v29, 0xc0135761
	v_mul_f32_e32 v30, v5, v5
	v_mul_f32_e32 v29, v0, v29
	v_fmaak_f32 v30, v255, v30, 0xc0135761
	v_mul_f32_e32 v30, v5, v30
	v_exp_f32_e32 v29, v29
	v_exp_f32_e32 v30, v30
	v_add_f32_e32 v28, 1.0, v32
	v_add_f32_e32 v29, 1.0, v29
	v_rcp_f32_e32 v31, v29
	v_add_f32_e32 v29, 1.0, v30
	v_rcp_f32_e32 v30, v29
	v_mul_f32_e32 v29, v1, v1
	v_fmaak_f32 v29, v255, v29, 0xc0135761
	v_mul_f32_e32 v29, v1, v29
	v_rcp_f32_e32 v28, v28
	v_exp_f32_e32 v32, v29
	v_mul_f32_e32 v34, v7, v7
	v_mul_f32_e32 v33, v2, v33
	v_mul_f32_e32 v29, v4, v28
	v_mul_f32_e32 v28, v0, v31
	v_add_f32_e32 v31, 1.0, v32
	v_mul_f32_e32 v32, v6, v6
	v_fmaak_f32 v34, v255, v34, 0xc0135761
	v_mul_f32_e32 v35, v3, v3
	v_fmaak_f32 v32, v255, v32, 0xc0135761
	v_mul_f32_e32 v34, v7, v34
	v_fmaak_f32 v35, v255, v35, 0xc0135761
	v_mul_f32_e32 v32, v6, v32
	v_mul_f32_e32 v35, v3, v35
	v_exp_f32_e32 v33, v33
	v_exp_f32_e32 v34, v34
	v_exp_f32_e32 v32, v32
	v_exp_f32_e32 v35, v35
	v_add_f32_e32 v33, 1.0, v33
	v_rcp_f32_e32 v36, v33
	v_add_f32_e32 v33, 1.0, v34
	v_add_f32_e32 v32, 1.0, v32
	v_rcp_f32_e32 v34, v33
	v_add_f32_e32 v33, 1.0, v35
	v_rcp_f32_e32 v31, v31
	v_rcp_f32_e32 v32, v32
	v_rcp_f32_e32 v37, v33
	v_mul_f32_e32 v30, v5, v30
	v_mul_f32_e32 v31, v1, v31
	v_mul_f32_e32 v33, v6, v32
	v_mul_f32_e32 v32, v2, v36
	v_mul_f32_e32 v35, v7, v34
	v_mul_f32_e32 v34, v3, v37
	s_andn2_b64 vcc, exec, s[84:85]
	v_cvt_pk_bf16_f32 v36, v29, v30
	v_cvt_pk_bf16_f32 v37, v33, v35
	v_cvt_pk_bf16_f32 v38, v28, v31
	v_cvt_pk_bf16_f32 v39, v32, v34
	global_store_dwordx4 v[40:41], v[36:39], off offset:256
	s_cbranch_vccnz .LBB0_702
	s_nop 0
	v_mul_f32_e32 v36, v18, v18
	v_mul_f32_e32 v37, v27, v27
	v_fmac_f32_e32 v36, v17, v17
	v_fmac_f32_e32 v37, v25, v25
	v_add_f32_e32 v36, v36, v37
	v_mul_f32_e32 v37, v19, v19
	v_mul_f32_e32 v38, v26, v26
	v_fmac_f32_e32 v37, v16, v16
	v_fmac_f32_e32 v38, v24, v24
	v_add_f32_e32 v17, v17, v18
	v_add_f32_e32 v18, v25, v27
	v_add_f32_e32 v37, v37, v38
	v_add_f32_e32 v17, v17, v18
	v_add_f32_e32 v16, v16, v19
	v_add_f32_e32 v18, v24, v26
	v_add_f32_e32 v36, v36, v37
	v_mul_f32_e32 v37, v30, v30
	v_mul_f32_e32 v38, v35, v35
	v_add_f32_e32 v16, v16, v18
	v_fmac_f32_e32 v37, v29, v29
	v_fmac_f32_e32 v38, v33, v33
	v_add_f32_e32 v16, v17, v16
	v_add_f32_e32 v17, v29, v30
	v_add_f32_e32 v18, v33, v35
	v_add_f32_e32 v37, v37, v38
	v_mul_f32_e32 v38, v31, v31
	v_mul_f32_e32 v39, v34, v34
	v_add_f32_e32 v17, v17, v18
	v_add_f32_e32 v18, v28, v31
	v_add_f32_e32 v19, v32, v34
	v_fmac_f32_e32 v38, v28, v28
	v_fmac_f32_e32 v39, v32, v32
	v_add_f32_e32 v18, v18, v19
	v_add_f32_e32 v17, v17, v18
	v_add_f32_e32 v18, v38, v39
	v_add_f32_e32 v16, 0, v16
	v_add_f32_e32 v18, v37, v18
	v_add_f32_e32 v16, v16, v17
	v_add_f32_e32 v19, v36, v18
	ds_swizzle_b32 v17, v16 offset:swizzle(SWAP,16)
	ds_swizzle_b32 v24, v19 offset:swizzle(SWAP,16)
	s_waitcnt lgkmcnt(0)
	v_add_f32_e32 v16, v16, v17
	v_add_f32_e32 v17, v19, v24
	v_mov_b32_e32 v18, v16
	v_mov_b32_e32 v19, v17
	s_nop 0
	v_permlane32_swap_b32_e32 v16, v18
	v_permlane32_swap_b32_e32 v17, v19
	s_and_saveexec_b64 s[6:7], s[4:5]
	s_cbranch_execz .LBB0_701
	v_pk_add_f32 v[16:17], v[16:17], v[18:19]
	v_lshlrev_b64 v[18:19], 6, v[20:21]
	v_lshl_add_u64 v[18:19], s[18:19], 0, v[18:19]
	v_lshl_add_u64 v[18:19], s[52:53], 3, v[18:19]
	s_lshl_b32 s52, s40, 3
	v_lshl_add_u64 v[18:19], v[18:19], 0, s[52:53]
	global_store_dwordx2 v[18:19], v[16:17], off
